# diag_final2x
# baseline (speedup 1.0000x reference)
; __device__ __forceinline__ float bf_lo(unsigned w) { return __uint_as_float(w << 16); }
; __device__ __forceinline__ float bf_hi(unsigned w) { return __uint_as_float(w & 0xffff0000u); }
; __device__ __forceinline__ float wave_sum(float v) {
; #pragma unroll
;     for (int o = 1; o < 64; o <<= 1) v += __shfl_xor(v, o);
;     return v;
; __device__ __forceinline__ void phase_final(const Params& p, int gw, int NGW, int lane) {
;     unsigned char* ws = p.ws;
;     const bf16_t* DN = (const bf16_t*)(ws + WS_SD); const float* SSQ = (const float*)(ws + WS_SSQ2); const bf16_t* H1 = (const bf16_t*)(ws + WS_SC);
;     const f32x4* g = (const f32x4*)p.in[25];
;     for (int row = gw; row < MT; row += NGW) {
;         const float r = rsqrtf(wave_sum(SSQ[(size_t)lane * MT + row]) * (1.f / DM) + EPSN);
;         const u32x2* dr = (const u32x2*)(DN + (size_t)row * DM) + lane; const u32x2* hr = (const u32x2*)(H1 + (size_t)row * DM) + lane; f32x4* o = (f32x4*)(p.out + (size_t)row * DM) + lane;
;         const f32x4* gp = g + lane;
;         asm volatile("" : "+v"(gp), "+v"(dr), "+v"(hr), "+v"(o));
; #pragma unroll 8
;         for (int j = 0; j < 16; ++j) { const u32x2 dw = dr[64 * j]; const f32x4 dn = {bf_lo(dw.x), bf_hi(dw.x), bf_lo(dw.y), bf_hi(dw.y)}; const u32x2 hw = hr[64 * j]; const f32x4 hh = {bf_lo(hw.x), bf_hi(hw.x), bf_lo(hw.y), bf_hi(hw.y)}; o[64 * j] = hh + dn * r * gp[64 * j]; }
.LBB0_1012:
	s_cmp_lt_i32 s96, 11
	s_cselect_b64 s[2:3], -1, 0
	s_and_b64 s[0:1], s[2:3], s[0:1]
	s_and_b64 s[0:1], s[0:1], s[10:11]
	s_andn2_b64 vcc, exec, s[0:1]
	s_cbranch_vccnz .LBB0_1017
	v_mbcnt_hi_u32_b32 v2, -1, v192
	v_and_b32_e32 v3, 64, v2
	v_add_u32_e32 v3, 64, v3
	v_xor_b32_e32 v4, 1, v2
	v_cmp_lt_i32_e32 vcc, v4, v3
	v_mov_b32_e32 v175, 0
	v_lshl_add_u64 v[0:1], s[58:59], 0, v[174:175]
	v_cndmask_b32_e32 v4, v2, v4, vcc
	v_lshlrev_b32_e32 v26, 2, v4
	v_xor_b32_e32 v4, 2, v2
	v_cmp_lt_i32_e32 vcc, v4, v3
	s_mov_b64 s[0:1], 0x314000
	v_mov_b32_e32 v179, v175
	v_cndmask_b32_e32 v4, v2, v4, vcc
	v_lshlrev_b32_e32 v27, 2, v4
	v_xor_b32_e32 v4, 4, v2
	v_cmp_lt_i32_e32 vcc, v4, v3
	v_lshl_add_u64 v[0:1], v[0:1], 0, s[0:1]
	s_mov_b64 s[0:1], 0x33114000
	v_cndmask_b32_e32 v4, v2, v4, vcc
	v_lshlrev_b32_e32 v28, 2, v4
	v_xor_b32_e32 v4, 8, v2
	v_cmp_lt_i32_e32 vcc, v4, v3
	v_mov_b32_e32 v177, v175
	v_lshl_add_u64 v[6:7], s[54:55], 0, v[176:177]
	v_cndmask_b32_e32 v4, v2, v4, vcc
	v_lshlrev_b32_e32 v29, 2, v4
	v_xor_b32_e32 v4, 16, v2
	v_cmp_lt_i32_e32 vcc, v4, v3
	v_lshl_add_u64 v[8:9], s[56:57], 0, v[176:177]
	v_mov_b32_e32 v32, 0x358637bd
	v_cndmask_b32_e32 v4, v2, v4, vcc
	v_lshlrev_b32_e32 v30, 2, v4
	v_xor_b32_e32 v4, 32, v2
	v_cmp_lt_i32_e32 vcc, v4, v3
	s_mov_b32 s4, 0x800000
	s_movk_i32 s5, 0x1000
	v_cndmask_b32_e32 v2, v2, v4, vcc
	s_waitcnt lgkmcnt(0)
	v_lshl_add_u64 v[4:5], s[58:59], 0, v[178:179]
	v_lshlrev_b32_e32 v31, 2, v2
	v_lshl_add_u64 v[2:3], v[4:5], 0, s[0:1]
	s_mov_b64 s[0:1], 0x2b114000
	v_lshl_add_u64 v[4:5], v[4:5], 0, s[0:1]
	s_mov_b64 s[0:1], 0x1000
	s_mov_b64 s[8:9], 0x2000
	s_mov_b64 s[12:13], 0x3000
	v_lshl_add_u64 v[2:3], v[2:3], 0, s[0:1]
	v_lshl_add_u64 v[4:5], v[4:5], 0, s[0:1]
	v_lshl_add_u64 v[8:9], v[8:9], 0, s[0:1]
	v_lshl_add_u64 v[36:37], v[6:7], 0, s[0:1]
	v_lshl_add_u64 v[38:39], v[6:7], 0, s[12:13]
	s_mov_b32 s21, s34
	s_mov_b32 s20, 0
.Lfin_diag_pass:
	s_ashr_i32 s35, s34, 31
	v_lshl_add_u64 v[10:11], s[34:35], 2, v[0:1]
	global_load_dword v33, v[10:11], off
	s_waitcnt vmcnt(0)
	ds_bpermute_b32 v11, v26, v33
	s_waitcnt lgkmcnt(0)
	v_add_f32_e32 v10, v33, v11
	ds_bpermute_b32 v11, v27, v10
	s_waitcnt lgkmcnt(0)
	v_add_f32_e32 v10, v10, v11
	ds_bpermute_b32 v11, v28, v10
	s_waitcnt lgkmcnt(0)
	v_add_f32_e32 v10, v10, v11
	ds_bpermute_b32 v11, v29, v10
	s_waitcnt lgkmcnt(0)
	v_add_f32_e32 v10, v10, v11
	ds_bpermute_b32 v11, v30, v10
	s_waitcnt lgkmcnt(0)
	v_add_f32_e32 v10, v10, v11
	ds_bpermute_b32 v11, v31, v10
	s_waitcnt lgkmcnt(0)
	v_add_f32_e32 v10, v10, v11
	v_fmamk_f32 v14, v10, 0x39800000, v32
	v_mul_f32_e32 v15, 0x4b800000, v14
	v_cmp_gt_f32_e32 vcc, s4, v14
	s_nop 1
	v_cndmask_b32_e32 v14, v14, v15, vcc
	v_rsq_f32_e32 v18, v14
	s_nop 0
	v_mul_f32_e32 v19, 0x45800000, v18
	v_cndmask_b32_e32 v18, v18, v19, vcc
	v_mov_b32_e32 v19, v18
.Lfin_row:
	s_ashr_i32 s35, s34, 31
	s_lshl_b64 s[2:3], s[34:35], 13
	s_lshl_b64 s[6:7], s[34:35], 14
	s_add_i32 s10, s34, s60
	s_min_i32 s10, s10, 0x1fff
	s_ashr_i32 s11, s10, 31
	v_lshl_add_u64 v[10:11], s[10:11], 2, v[0:1]
	v_lshl_add_u64 v[12:13], v[2:3], 0, s[2:3]
	v_lshl_add_u64 v[14:15], v[4:5], 0, s[2:3]
	v_lshl_add_u64 v[16:17], v[8:9], 0, s[6:7]
	global_load_dword v33, v[10:11], off
	v_lshl_add_u64 v[22:23], v[16:17], 0, s[8:9]
	global_load_dwordx2 v[64:65], v[12:13], off offset:-4096 nt
	global_load_dwordx2 v[96:97], v[14:15], off offset:-4096 nt
	global_load_dwordx4 v[128:131], v[36:37], off offset:-4096
	global_load_dwordx2 v[66:67], v[12:13], off offset:-3584 nt
	global_load_dwordx2 v[98:99], v[14:15], off offset:-3584 nt
	global_load_dwordx4 v[132:135], v[36:37], off offset:-3072
	global_load_dwordx2 v[68:69], v[12:13], off offset:-3072 nt
	global_load_dwordx2 v[100:101], v[14:15], off offset:-3072 nt
	global_load_dwordx4 v[136:139], v[36:37], off offset:-2048
	global_load_dwordx2 v[70:71], v[12:13], off offset:-2560 nt
	global_load_dwordx2 v[102:103], v[14:15], off offset:-2560 nt
	global_load_dwordx4 v[140:143], v[36:37], off offset:-1024
	global_load_dwordx2 v[72:73], v[12:13], off offset:-2048 nt
	global_load_dwordx2 v[104:105], v[14:15], off offset:-2048 nt
	global_load_dwordx4 v[144:147], v[36:37], off
	global_load_dwordx2 v[74:75], v[12:13], off offset:-1536 nt
	global_load_dwordx2 v[106:107], v[14:15], off offset:-1536 nt
	global_load_dwordx4 v[148:151], v[36:37], off offset:1024
	global_load_dwordx2 v[76:77], v[12:13], off offset:-1024 nt
	global_load_dwordx2 v[108:109], v[14:15], off offset:-1024 nt
	global_load_dwordx4 v[152:155], v[36:37], off offset:2048
	global_load_dwordx2 v[78:79], v[12:13], off offset:-512 nt
	global_load_dwordx2 v[110:111], v[14:15], off offset:-512 nt
	global_load_dwordx4 v[156:159], v[36:37], off offset:3072
	global_load_dwordx2 v[80:81], v[12:13], off nt
	global_load_dwordx2 v[112:113], v[14:15], off nt
	global_load_dwordx4 v[160:163], v[38:39], off offset:-4096
	global_load_dwordx2 v[82:83], v[12:13], off offset:512 nt
	global_load_dwordx2 v[114:115], v[14:15], off offset:512 nt
	global_load_dwordx4 v[164:167], v[38:39], off offset:-3072
	global_load_dwordx2 v[84:85], v[12:13], off offset:1024 nt
	global_load_dwordx2 v[116:117], v[14:15], off offset:1024 nt
	global_load_dwordx4 v[168:171], v[38:39], off offset:-2048
	global_load_dwordx2 v[86:87], v[12:13], off offset:1536 nt
	global_load_dwordx2 v[118:119], v[14:15], off offset:1536 nt
	global_load_dwordx4 v[172:175], v[38:39], off offset:-1024
	global_load_dwordx2 v[88:89], v[12:13], off offset:2048 nt
	global_load_dwordx2 v[120:121], v[14:15], off offset:2048 nt
	global_load_dwordx4 v[176:179], v[38:39], off
	global_load_dwordx2 v[90:91], v[12:13], off offset:2560 nt
	global_load_dwordx2 v[122:123], v[14:15], off offset:2560 nt
	global_load_dwordx4 v[180:183], v[38:39], off offset:1024
	global_load_dwordx2 v[92:93], v[12:13], off offset:3072 nt
	global_load_dwordx2 v[124:125], v[14:15], off offset:3072 nt
	global_load_dwordx4 v[184:187], v[38:39], off offset:2048
	global_load_dwordx2 v[94:95], v[12:13], off offset:3584 nt
	global_load_dwordx2 v[126:127], v[14:15], off offset:3584 nt
	global_load_dwordx4 v[188:191], v[38:39], off offset:3072
	s_waitcnt vmcnt(45)
; __device__ __forceinline__ float bf_lo(unsigned w) { return __uint_as_float(w << 16); }
; __device__ __forceinline__ float bf_hi(unsigned w) { return __uint_as_float(w & 0xffff0000u); }
; __device__ __forceinline__ void phase_final(const Params& p, int gw, int NGW, int lane) {
;     ...
;         for (int j = 0; j < 16; ++j) { const u32x2 dw = dr[64 * j]; const f32x4 dn = {bf_lo(dw.x), bf_hi(dw.x), bf_lo(dw.y), bf_hi(dw.y)}; const u32x2 hw = hr[64 * j]; const f32x4 hh = {bf_lo(hw.x), bf_hi(hw.x), bf_lo(hw.y), bf_hi(hw.y)}; o[64 * j] = hh + dn * r * gp[64 * j]; }
	v_lshlrev_b32_e32 v40, 16, v64
	v_and_b32_e32 v41, 0xffff0000, v64
	v_lshlrev_b32_e32 v42, 16, v65
	v_and_b32_e32 v43, 0xffff0000, v65
	v_lshlrev_b32_e32 v44, 16, v96
	v_and_b32_e32 v45, 0xffff0000, v96
	v_lshlrev_b32_e32 v46, 16, v97
	v_and_b32_e32 v47, 0xffff0000, v97
	v_pk_mul_f32 v[40:41], v[18:19], v[40:41]
	v_pk_mul_f32 v[42:43], v[18:19], v[42:43]
	v_pk_fma_f32 v[128:129], v[128:129], v[40:41], v[44:45]
	v_pk_fma_f32 v[130:131], v[130:131], v[42:43], v[46:47]
	global_store_dwordx4 v[16:17], v[128:131], off offset:-4096 nt
	s_waitcnt vmcnt(43)
	v_lshlrev_b32_e32 v48, 16, v66
	v_and_b32_e32 v49, 0xffff0000, v66
	v_lshlrev_b32_e32 v50, 16, v67
	v_and_b32_e32 v51, 0xffff0000, v67
	v_lshlrev_b32_e32 v52, 16, v98
	v_and_b32_e32 v53, 0xffff0000, v98
	v_lshlrev_b32_e32 v54, 16, v99
	v_and_b32_e32 v55, 0xffff0000, v99
	v_pk_mul_f32 v[48:49], v[18:19], v[48:49]
	v_pk_mul_f32 v[50:51], v[18:19], v[50:51]
	v_pk_fma_f32 v[132:133], v[132:133], v[48:49], v[52:53]
	v_pk_fma_f32 v[134:135], v[134:135], v[50:51], v[54:55]
	global_store_dwordx4 v[16:17], v[132:135], off offset:-3072 nt
	s_waitcnt vmcnt(41)
	v_lshlrev_b32_e32 v40, 16, v68
	v_and_b32_e32 v41, 0xffff0000, v68
	v_lshlrev_b32_e32 v42, 16, v69
	v_and_b32_e32 v43, 0xffff0000, v69
	v_lshlrev_b32_e32 v44, 16, v100
	v_and_b32_e32 v45, 0xffff0000, v100
	v_lshlrev_b32_e32 v46, 16, v101
	v_and_b32_e32 v47, 0xffff0000, v101
	v_pk_mul_f32 v[40:41], v[18:19], v[40:41]
	v_pk_mul_f32 v[42:43], v[18:19], v[42:43]
	v_pk_fma_f32 v[136:137], v[136:137], v[40:41], v[44:45]
	v_pk_fma_f32 v[138:139], v[138:139], v[42:43], v[46:47]
	global_store_dwordx4 v[16:17], v[136:139], off offset:-2048 nt
	s_waitcnt vmcnt(39)
	v_lshlrev_b32_e32 v48, 16, v70
	v_and_b32_e32 v49, 0xffff0000, v70
	v_lshlrev_b32_e32 v50, 16, v71
	v_and_b32_e32 v51, 0xffff0000, v71
	v_lshlrev_b32_e32 v52, 16, v102
	v_and_b32_e32 v53, 0xffff0000, v102
	v_lshlrev_b32_e32 v54, 16, v103
	v_and_b32_e32 v55, 0xffff0000, v103
	v_pk_mul_f32 v[48:49], v[18:19], v[48:49]
	v_pk_mul_f32 v[50:51], v[18:19], v[50:51]
	v_pk_fma_f32 v[140:141], v[140:141], v[48:49], v[52:53]
	v_pk_fma_f32 v[142:143], v[142:143], v[50:51], v[54:55]
	global_store_dwordx4 v[16:17], v[140:143], off offset:-1024 nt
	s_waitcnt vmcnt(37)
	v_lshlrev_b32_e32 v40, 16, v72
	v_and_b32_e32 v41, 0xffff0000, v72
	v_lshlrev_b32_e32 v42, 16, v73
	v_and_b32_e32 v43, 0xffff0000, v73
	v_lshlrev_b32_e32 v44, 16, v104
	v_and_b32_e32 v45, 0xffff0000, v104
	v_lshlrev_b32_e32 v46, 16, v105
	v_and_b32_e32 v47, 0xffff0000, v105
	v_pk_mul_f32 v[40:41], v[18:19], v[40:41]
	v_pk_mul_f32 v[42:43], v[18:19], v[42:43]
	v_pk_fma_f32 v[144:145], v[144:145], v[40:41], v[44:45]
	v_pk_fma_f32 v[146:147], v[146:147], v[42:43], v[46:47]
	global_store_dwordx4 v[16:17], v[144:147], off nt
	s_waitcnt vmcnt(35)
	v_lshlrev_b32_e32 v48, 16, v74
	v_and_b32_e32 v49, 0xffff0000, v74
	v_lshlrev_b32_e32 v50, 16, v75
	v_and_b32_e32 v51, 0xffff0000, v75
	v_lshlrev_b32_e32 v52, 16, v106
	v_and_b32_e32 v53, 0xffff0000, v106
	v_lshlrev_b32_e32 v54, 16, v107
	v_and_b32_e32 v55, 0xffff0000, v107
	v_pk_mul_f32 v[48:49], v[18:19], v[48:49]
	v_pk_mul_f32 v[50:51], v[18:19], v[50:51]
	v_pk_fma_f32 v[148:149], v[148:149], v[48:49], v[52:53]
	v_pk_fma_f32 v[150:151], v[150:151], v[50:51], v[54:55]
	global_store_dwordx4 v[16:17], v[148:151], off offset:1024 nt
	s_waitcnt vmcnt(33)
	v_lshlrev_b32_e32 v40, 16, v76
	v_and_b32_e32 v41, 0xffff0000, v76
	v_lshlrev_b32_e32 v42, 16, v77
	v_and_b32_e32 v43, 0xffff0000, v77
	v_lshlrev_b32_e32 v44, 16, v108
	v_and_b32_e32 v45, 0xffff0000, v108
	v_lshlrev_b32_e32 v46, 16, v109
	v_and_b32_e32 v47, 0xffff0000, v109
	v_pk_mul_f32 v[40:41], v[18:19], v[40:41]
	v_pk_mul_f32 v[42:43], v[18:19], v[42:43]
	v_pk_fma_f32 v[152:153], v[152:153], v[40:41], v[44:45]
	v_pk_fma_f32 v[154:155], v[154:155], v[42:43], v[46:47]
	global_store_dwordx4 v[16:17], v[152:155], off offset:2048 nt
	s_waitcnt vmcnt(31)
	v_lshlrev_b32_e32 v48, 16, v78
	v_and_b32_e32 v49, 0xffff0000, v78
	v_lshlrev_b32_e32 v50, 16, v79
	v_and_b32_e32 v51, 0xffff0000, v79
	v_lshlrev_b32_e32 v52, 16, v110
	v_and_b32_e32 v53, 0xffff0000, v110
	v_lshlrev_b32_e32 v54, 16, v111
	v_and_b32_e32 v55, 0xffff0000, v111
	v_pk_mul_f32 v[48:49], v[18:19], v[48:49]
	v_pk_mul_f32 v[50:51], v[18:19], v[50:51]
	v_pk_fma_f32 v[156:157], v[156:157], v[48:49], v[52:53]
	v_pk_fma_f32 v[158:159], v[158:159], v[50:51], v[54:55]
	global_store_dwordx4 v[16:17], v[156:159], off offset:3072 nt
	s_waitcnt vmcnt(29)
	v_lshlrev_b32_e32 v40, 16, v80
	v_and_b32_e32 v41, 0xffff0000, v80
	v_lshlrev_b32_e32 v42, 16, v81
	v_and_b32_e32 v43, 0xffff0000, v81
	v_lshlrev_b32_e32 v44, 16, v112
	v_and_b32_e32 v45, 0xffff0000, v112
	v_lshlrev_b32_e32 v46, 16, v113
	v_and_b32_e32 v47, 0xffff0000, v113
	v_pk_mul_f32 v[40:41], v[18:19], v[40:41]
	v_pk_mul_f32 v[42:43], v[18:19], v[42:43]
	v_pk_fma_f32 v[160:161], v[160:161], v[40:41], v[44:45]
	v_pk_fma_f32 v[162:163], v[162:163], v[42:43], v[46:47]
	global_store_dwordx4 v[22:23], v[160:163], off offset:-4096 nt
	s_waitcnt vmcnt(27)
; __device__ __forceinline__ float bf_lo(unsigned w) { return __uint_as_float(w << 16); }
; __device__ __forceinline__ float bf_hi(unsigned w) { return __uint_as_float(w & 0xffff0000u); }
; __device__ __forceinline__ float wave_sum(float v) {
; #pragma unroll
;     for (int o = 1; o < 64; o <<= 1) v += __shfl_xor(v, o);
;     return v;
; __device__ __forceinline__ void phase_final(const Params& p, int gw, int NGW, int lane) {
;     ...
;     for (int row = gw; row < MT; row += NGW) {
;         const float r = rsqrtf(wave_sum(SSQ[(size_t)lane * MT + row]) * (1.f / DM) + EPSN);
;         const u32x2* dr = (const u32x2*)(DN + (size_t)row * DM) + lane; const u32x2* hr = (const u32x2*)(H1 + (size_t)row * DM) + lane; f32x4* o = (f32x4*)(p.out + (size_t)row * DM) + lane;
;         const f32x4* gp = g + lane;
;         asm volatile("" : "+v"(gp), "+v"(dr), "+v"(hr), "+v"(o));
; #pragma unroll 8
;         for (int j = 0; j < 16; ++j) { const u32x2 dw = dr[64 * j]; const f32x4 dn = {bf_lo(dw.x), bf_hi(dw.x), bf_lo(dw.y), bf_hi(dw.y)}; const u32x2 hw = hr[64 * j]; const f32x4 hh = {bf_lo(hw.x), bf_hi(hw.x), bf_lo(hw.y), bf_hi(hw.y)}; o[64 * j] = hh + dn * r * gp[64 * j]; }
	v_lshlrev_b32_e32 v48, 16, v82
	v_and_b32_e32 v49, 0xffff0000, v82
	v_lshlrev_b32_e32 v50, 16, v83
	v_and_b32_e32 v51, 0xffff0000, v83
	v_lshlrev_b32_e32 v52, 16, v114
	v_and_b32_e32 v53, 0xffff0000, v114
	v_lshlrev_b32_e32 v54, 16, v115
	v_and_b32_e32 v55, 0xffff0000, v115
	v_pk_mul_f32 v[48:49], v[18:19], v[48:49]
	v_pk_mul_f32 v[50:51], v[18:19], v[50:51]
	v_pk_fma_f32 v[164:165], v[164:165], v[48:49], v[52:53]
	v_pk_fma_f32 v[166:167], v[166:167], v[50:51], v[54:55]
	global_store_dwordx4 v[22:23], v[164:167], off offset:-3072 nt
	s_waitcnt vmcnt(25)
	v_lshlrev_b32_e32 v40, 16, v84
	v_and_b32_e32 v41, 0xffff0000, v84
	v_lshlrev_b32_e32 v42, 16, v85
	v_and_b32_e32 v43, 0xffff0000, v85
	v_lshlrev_b32_e32 v44, 16, v116
	v_and_b32_e32 v45, 0xffff0000, v116
	v_lshlrev_b32_e32 v46, 16, v117
	v_and_b32_e32 v47, 0xffff0000, v117
	v_pk_mul_f32 v[40:41], v[18:19], v[40:41]
	v_pk_mul_f32 v[42:43], v[18:19], v[42:43]
	v_pk_fma_f32 v[168:169], v[168:169], v[40:41], v[44:45]
	v_pk_fma_f32 v[170:171], v[170:171], v[42:43], v[46:47]
	global_store_dwordx4 v[22:23], v[168:171], off offset:-2048 nt
	s_waitcnt vmcnt(23)
	v_lshlrev_b32_e32 v48, 16, v86
	v_and_b32_e32 v49, 0xffff0000, v86
	v_lshlrev_b32_e32 v50, 16, v87
	v_and_b32_e32 v51, 0xffff0000, v87
	v_lshlrev_b32_e32 v52, 16, v118
	v_and_b32_e32 v53, 0xffff0000, v118
	v_lshlrev_b32_e32 v54, 16, v119
	v_and_b32_e32 v55, 0xffff0000, v119
	v_pk_mul_f32 v[48:49], v[18:19], v[48:49]
	v_pk_mul_f32 v[50:51], v[18:19], v[50:51]
	v_pk_fma_f32 v[172:173], v[172:173], v[48:49], v[52:53]
	v_pk_fma_f32 v[174:175], v[174:175], v[50:51], v[54:55]
	global_store_dwordx4 v[22:23], v[172:175], off offset:-1024 nt
	s_waitcnt vmcnt(21)
	v_lshlrev_b32_e32 v40, 16, v88
	v_and_b32_e32 v41, 0xffff0000, v88
	v_lshlrev_b32_e32 v42, 16, v89
	v_and_b32_e32 v43, 0xffff0000, v89
	v_lshlrev_b32_e32 v44, 16, v120
	v_and_b32_e32 v45, 0xffff0000, v120
	v_lshlrev_b32_e32 v46, 16, v121
	v_and_b32_e32 v47, 0xffff0000, v121
	v_pk_mul_f32 v[40:41], v[18:19], v[40:41]
	v_pk_mul_f32 v[42:43], v[18:19], v[42:43]
	v_pk_fma_f32 v[176:177], v[176:177], v[40:41], v[44:45]
	v_pk_fma_f32 v[178:179], v[178:179], v[42:43], v[46:47]
	global_store_dwordx4 v[22:23], v[176:179], off nt
	s_waitcnt vmcnt(19)
	v_lshlrev_b32_e32 v48, 16, v90
	v_and_b32_e32 v49, 0xffff0000, v90
	v_lshlrev_b32_e32 v50, 16, v91
	v_and_b32_e32 v51, 0xffff0000, v91
	v_lshlrev_b32_e32 v52, 16, v122
	v_and_b32_e32 v53, 0xffff0000, v122
	v_lshlrev_b32_e32 v54, 16, v123
	v_and_b32_e32 v55, 0xffff0000, v123
	v_pk_mul_f32 v[48:49], v[18:19], v[48:49]
	v_pk_mul_f32 v[50:51], v[18:19], v[50:51]
	v_pk_fma_f32 v[180:181], v[180:181], v[48:49], v[52:53]
	v_pk_fma_f32 v[182:183], v[182:183], v[50:51], v[54:55]
	global_store_dwordx4 v[22:23], v[180:183], off offset:1024 nt
	s_waitcnt vmcnt(17)
	v_lshlrev_b32_e32 v40, 16, v92
	v_and_b32_e32 v41, 0xffff0000, v92
	v_lshlrev_b32_e32 v42, 16, v93
	v_and_b32_e32 v43, 0xffff0000, v93
	v_lshlrev_b32_e32 v44, 16, v124
	v_and_b32_e32 v45, 0xffff0000, v124
	v_lshlrev_b32_e32 v46, 16, v125
	v_and_b32_e32 v47, 0xffff0000, v125
	v_pk_mul_f32 v[40:41], v[18:19], v[40:41]
	v_pk_mul_f32 v[42:43], v[18:19], v[42:43]
	v_pk_fma_f32 v[184:185], v[184:185], v[40:41], v[44:45]
	v_pk_fma_f32 v[186:187], v[186:187], v[42:43], v[46:47]
	global_store_dwordx4 v[22:23], v[184:187], off offset:2048 nt
	s_waitcnt vmcnt(15)
	v_lshlrev_b32_e32 v48, 16, v94
	v_and_b32_e32 v49, 0xffff0000, v94
	v_lshlrev_b32_e32 v50, 16, v95
	v_and_b32_e32 v51, 0xffff0000, v95
	v_lshlrev_b32_e32 v52, 16, v126
	v_and_b32_e32 v53, 0xffff0000, v126
	v_lshlrev_b32_e32 v54, 16, v127
	v_and_b32_e32 v55, 0xffff0000, v127
	v_pk_mul_f32 v[48:49], v[18:19], v[48:49]
	v_pk_mul_f32 v[50:51], v[18:19], v[50:51]
	v_pk_fma_f32 v[188:189], v[188:189], v[48:49], v[52:53]
	v_pk_fma_f32 v[190:191], v[190:191], v[50:51], v[54:55]
	global_store_dwordx4 v[22:23], v[188:191], off offset:3072 nt
	ds_bpermute_b32 v11, v26, v33
	s_waitcnt lgkmcnt(0)
	v_add_f32_e32 v10, v33, v11
	ds_bpermute_b32 v11, v27, v10
	s_waitcnt lgkmcnt(0)
	v_add_f32_e32 v10, v10, v11
	ds_bpermute_b32 v11, v28, v10
	s_waitcnt lgkmcnt(0)
	v_add_f32_e32 v10, v10, v11
	ds_bpermute_b32 v11, v29, v10
	s_waitcnt lgkmcnt(0)
	v_add_f32_e32 v10, v10, v11
	ds_bpermute_b32 v11, v30, v10
	s_waitcnt lgkmcnt(0)
	v_add_f32_e32 v10, v10, v11
	ds_bpermute_b32 v11, v31, v10
	s_waitcnt lgkmcnt(0)
	v_add_f32_e32 v10, v10, v11
	v_fmamk_f32 v14, v10, 0x39800000, v32
	v_mul_f32_e32 v15, 0x4b800000, v14
	v_cmp_gt_f32_e32 vcc, s4, v14
	s_nop 1
	v_cndmask_b32_e32 v14, v14, v15, vcc
	v_rsq_f32_e32 v18, v14
	s_nop 0
	v_mul_f32_e32 v19, 0x45800000, v18
	v_cndmask_b32_e32 v18, v18, v19, vcc
	v_mov_b32_e32 v19, v18
	s_add_i32 s34, s34, s60
	s_cmpk_gt_i32 s34, 0x1fff
	s_cbranch_scc0 .Lfin_row
	s_cmp_eq_u32 s20, 0
	s_cbranch_scc0 .LBB0_1017
	s_mov_b32 s20, 1
	s_mov_b32 s34, s21
	s_branch .Lfin_diag_pass
